# MLA output stores also widened to 16-byte via v_permlane32_swap (all four attention store sites now dwordx4)
# baseline (speedup 1.0000x reference)
; DI int otid() { int t = threadIdx.x; asm volatile("" : "+v"(t)); return t; }
; DI void store_o(bf16_t* dst  , const f32x16& o0, const f32x16& o1, int h) {
; #pragma unroll
;   for (int g = 0; g < 4; ++g) {
;     uint2 u;
;     u.x = pk_bf16(o0[4 * g], o0[4 * g + 1]); u.y = pk_bf16(o0[4 * g + 2], o0[4 * g + 3]);
;     *(uint2*)(dst + 8 * g + 4 * h) = u;
;     u.x = pk_bf16(o1[4 * g], o1[4 * g + 1]); u.y = pk_bf16(o1[4 * g + 2], o1[4 * g + 3]);
;     *(uint2*)(dst + 32 + 8 * g + 4 * h) = u;
;   }
; }
; DI void phase_attn(const Params& p, int layer, char* smem) {
;     ...
; #pragma unroll
;         for (int i = 0; i < 16; ++i) { ssqA += o0[i] * o0[i] + o1[i] * o1[i]; ssqB += u0[i] * u0[i] + u1[i] * u1[i]; }
;         const int tid2 = otid(), tA = b * SEQ + q5 * 512 + (tid2 >> 6) * 64 + (tid2 & 31), h2 = (tid2 >> 5) & 1;
;         store_o(ocat + (size_t)tA * 1024 + 256 + hd * 64, o0, o1, h2);
;         store_o(ocat + (size_t)(tA + 32) * 1024 + 256 + hd * 64, u0, u1, h2);
.LBB0_350:
	v_mul_f32_e32 v83, v65, v0
	v_mul_f32_e32 v85, v0, v33
	v_mul_f32_e32 v0, v34, v34
	v_fmac_f32_e32 v0, v2, v2
	v_mul_f32_e32 v26, v35, v35
	v_add_f32_e32 v0, v172, v0
	v_mul_f32_e32 v24, v18, v18
	v_fmac_f32_e32 v26, v3, v3
	v_fmac_f32_e32 v24, v50, v50
	v_add_f32_e32 v0, v26, v0
	v_mul_f32_e32 v26, v19, v19
	v_add_f32_e32 v24, v173, v24
	v_fmac_f32_e32 v26, v51, v51
	v_add_f32_e32 v24, v26, v24
	v_mul_f32_e32 v26, v36, v36
	v_fmac_f32_e32 v26, v4, v4
	v_add_f32_e32 v0, v26, v0
	v_mul_f32_e32 v26, v20, v20
	v_fmac_f32_e32 v26, v52, v52
	v_add_f32_e32 v24, v26, v24
	v_mul_f32_e32 v26, v37, v37
	v_fmac_f32_e32 v26, v5, v5
	v_add_f32_e32 v0, v26, v0
	v_mul_f32_e32 v26, v21, v21
	v_fmac_f32_e32 v26, v53, v53
	v_add_f32_e32 v24, v26, v24
	v_mul_f32_e32 v26, v38, v38
	v_fmac_f32_e32 v26, v6, v6
	v_add_f32_e32 v86, v26, v0
	v_mul_f32_e32 v0, v22, v22
	v_fmac_f32_e32 v0, v54, v54
	v_mul_f32_e32 v88, v39, v39
	v_mul_f32_e32 v89, v23, v23
	v_add_f32_e32 v87, v0, v24
	v_fmac_f32_e32 v88, v7, v7
	v_fmac_f32_e32 v89, v55, v55
	v_mul_f32_e32 v90, v40, v40
	v_mul_f32_e32 v92, v8, v8
	v_mul_f32_e32 v93, v64, v64
	v_mul_f32_e32 v91, v32, v32
	v_pk_add_f32 v[86:87], v[88:89], v[86:87]
	v_pk_add_f32 v[88:89], v[92:93], v[90:91]
	v_mov_b32_e32 v24, v41
	v_pk_add_f32 v[86:87], v[88:89], v[86:87]
	v_mov_b32_e32 v66, v9
	v_pk_mul_f32 v[88:89], v[24:25], v[24:25]
	v_mov_b32_e32 v74, v42
	v_pk_fma_f32 v[88:89], v[66:67], v[66:67], v[88:89]
	v_mov_b32_e32 v80, v10
	v_pk_add_f32 v[86:87], v[88:89], v[86:87]
	v_pk_mul_f32 v[88:89], v[74:75], v[74:75]
	v_mov_b32_e32 v26, v43
	v_pk_fma_f32 v[88:89], v[80:81], v[80:81], v[88:89]
	v_mov_b32_e32 v58, v11
	v_pk_add_f32 v[86:87], v[88:89], v[86:87]
	v_pk_mul_f32 v[88:89], v[26:27], v[26:27]
	v_mov_b32_e32 v72, v44
	v_pk_fma_f32 v[88:89], v[58:59], v[58:59], v[88:89]
	v_mov_b32_e32 v78, v12
	v_pk_add_f32 v[86:87], v[88:89], v[86:87]
	v_pk_mul_f32 v[88:89], v[72:73], v[72:73]
	v_mov_b32_e32 v28, v45
	v_pk_fma_f32 v[88:89], v[78:79], v[78:79], v[88:89]
	v_mov_b32_e32 v60, v13
	v_pk_add_f32 v[86:87], v[88:89], v[86:87]
	v_pk_mul_f32 v[88:89], v[28:29], v[28:29]
	v_mov_b32_e32 v70, v46
	v_pk_fma_f32 v[88:89], v[60:61], v[60:61], v[88:89]
	v_mov_b32_e32 v76, v14
	v_pk_add_f32 v[86:87], v[88:89], v[86:87]
	v_pk_mul_f32 v[88:89], v[70:71], v[70:71]
	v_mov_b32_e32 v30, v47
	v_pk_fma_f32 v[88:89], v[76:77], v[76:77], v[88:89]
	v_mov_b32_e32 v62, v15
	v_pk_add_f32 v[86:87], v[88:89], v[86:87]
	v_pk_mul_f32 v[88:89], v[30:31], v[30:31]
	v_mov_b32_e32 v56, v48
	v_pk_fma_f32 v[88:89], v[62:63], v[62:63], v[88:89]
	v_mov_b32_e32 v68, v16
	v_pk_add_f32 v[86:87], v[88:89], v[86:87]
	v_pk_mul_f32 v[88:89], v[56:57], v[56:57]
	v_mov_b32_e32 v84, v49
	v_pk_fma_f32 v[88:89], v[68:69], v[68:69], v[88:89]
	v_mov_b32_e32 v0, v228
	v_pk_add_f32 v[86:87], v[88:89], v[86:87]
	v_mov_b32_e32 v82, v17
	v_pk_mul_f32 v[88:89], v[84:85], v[84:85]
	s_lshl_b32 s34, s38, 7
	v_and_b32_e32 v24, 0xffffffc0, v0
	v_pk_fma_f32 v[88:89], v[82:83], v[82:83], v[88:89]
	v_add_u32_e32 v24, s44, v24
	v_pk_add_f32 v[172:173], v[88:89], v[86:87]
	v_and_or_b32 v86, v0, 31, v24
	v_ashrrev_i32_e32 v87, 31, v86
	v_lshlrev_b64 v[88:89], 11, v[86:87]
	v_lshl_add_u64 v[88:89], s[66:67], 0, v[88:89]
	v_lshrrev_b32_e32 v0, 2, v0
	v_lshl_add_u64 v[88:89], v[88:89], 0, s[34:35]
	v_and_b32_e32 v0, 8, v0
	v_lshl_add_u64 v[88:89], v[88:89], 0, v[0:1]
	v_lshl_add_u64 v[88:89], v[88:89], 0, v[0:1]
	v_cvt_pk_bf16_f32 v34, v34, v35
	v_cvt_pk_bf16_f32 v35, v36, v37
	v_cvt_pk_bf16_f32 v36, v38, v39
	v_cvt_pk_bf16_f32 v37, v40, v41
	v_cvt_pk_bf16_f32 v42, v42, v43
	v_cvt_pk_bf16_f32 v43, v44, v45
	v_cvt_pk_bf16_f32 v44, v46, v47
	v_cvt_pk_bf16_f32 v45, v48, v49
	v_cvt_pk_bf16_f32 v2, v2, v3
	v_cvt_pk_bf16_f32 v3, v4, v5
	v_cvt_pk_bf16_f32 v4, v6, v7
	v_cvt_pk_bf16_f32 v5, v8, v9
	v_cvt_pk_bf16_f32 v10, v10, v11
	v_cvt_pk_bf16_f32 v11, v12, v13
	v_cvt_pk_bf16_f32 v12, v14, v15
	v_cvt_pk_bf16_f32 v13, v16, v17
	s_nop 1
	v_permlane32_swap_b32_e32 v34, v36
	v_permlane32_swap_b32_e32 v35, v37
	v_permlane32_swap_b32_e32 v42, v44
	v_permlane32_swap_b32_e32 v43, v45
	v_permlane32_swap_b32_e32 v2, v4
	v_permlane32_swap_b32_e32 v3, v5
	v_permlane32_swap_b32_e32 v10, v12
	v_permlane32_swap_b32_e32 v11, v13
	global_store_dwordx4 v[88:89], v[34:37], off offset:512
	global_store_dwordx4 v[88:89], v[42:45], off offset:544
	global_store_dwordx4 v[88:89], v[2:5], off offset:576
	global_store_dwordx4 v[88:89], v[10:13], off offset:608
	v_or_b32_e32 v6, 32, v86
	v_ashrrev_i32_e32 v7, 31, v6
	v_lshlrev_b64 v[6:7], 11, v[6:7]
	v_lshl_add_u64 v[6:7], s[66:67], 0, v[6:7]
	v_lshl_add_u64 v[6:7], v[6:7], 0, s[34:35]
	v_lshl_add_u64 v[6:7], v[6:7], 0, v[0:1]
	v_lshl_add_u64 v[6:7], v[6:7], 0, v[0:1]
	v_cvt_pk_bf16_f32 v50, v50, v51
	v_cvt_pk_bf16_f32 v51, v52, v53
	v_cvt_pk_bf16_f32 v52, v54, v55
	v_cvt_pk_bf16_f32 v53, v64, v67
	v_cvt_pk_bf16_f32 v14, v81, v59
	v_cvt_pk_bf16_f32 v15, v79, v61
	v_cvt_pk_bf16_f32 v16, v77, v63
	v_cvt_pk_bf16_f32 v17, v69, v83
	v_cvt_pk_bf16_f32 v18, v18, v19
	v_cvt_pk_bf16_f32 v19, v20, v21
	v_cvt_pk_bf16_f32 v20, v22, v23
	v_cvt_pk_bf16_f32 v21, v32, v25
	v_cvt_pk_bf16_f32 v22, v75, v27
	v_cvt_pk_bf16_f32 v23, v73, v29
	v_cvt_pk_bf16_f32 v24, v71, v31
	v_cvt_pk_bf16_f32 v25, v57, v85
	s_nop 1
	v_permlane32_swap_b32_e32 v50, v52
	v_permlane32_swap_b32_e32 v51, v53
	v_permlane32_swap_b32_e32 v14, v16
	v_permlane32_swap_b32_e32 v15, v17
	v_permlane32_swap_b32_e32 v18, v20
	v_permlane32_swap_b32_e32 v19, v21
	v_permlane32_swap_b32_e32 v22, v24
	v_permlane32_swap_b32_e32 v23, v25
	global_store_dwordx4 v[6:7], v[50:53], off offset:512
	global_store_dwordx4 v[6:7], v[14:17], off offset:544
	global_store_dwordx4 v[6:7], v[18:21], off offset:576
	global_store_dwordx4 v[6:7], v[22:25], off offset:608
	s_add_i32 s38, s38, 1
	s_add_u32 s10, s10, 0x800000
	s_addc_u32 s11, s11, 0
	s_cmp_eq_u32 s38, 4
	s_nop 1
	s_cbranch_scc1 .LBB0_381
